# rope / qk-norm phase: all loads of a row (grouped-query blocks, first gain word, second differential pass) issued together at the top of the row iteration instead of one wait per group
# baseline (speedup 1.0000x reference)
.LBB0_992:
	s_ashr_i32 s3, s2, 31
	s_lshl_b64 s[4:5], s[2:3], 13
	v_readlane_b32 s20, v253, 56
	v_readlane_b32 s21, v253, 57
	s_add_u32 s20, s20, s4
	s_addc_u32 s21, s21, s5
	v_lshl_add_u64 v[116:117], s[20:21], 0, v[176:177]
	v_mov_b32_e32 v119, v177
	v_mov_b32_e32 v118, v12
	v_lshl_add_u64 v[116:117], v[116:117], 0, v[118:119]
	v_mov_b32_e32 v118, v14
	v_lshl_add_u64 v[116:117], v[116:117], 0, v[118:119]
	s_mov_b64 s[22:23], 0x1600
	v_lshl_add_u64 v[120:121], v[116:117], 0, s[22:23]
	s_mov_b64 s[22:23], 0x1000
	v_lshl_add_u64 v[116:117], v[116:117], 0, s[22:23]
	global_load_dwordx4 v[100:103], v[116:117], off offset:1536
	global_load_dwordx4 v[104:107], v[120:121], off offset:64
	global_load_dword v124, v[8:9], off
	s_mul_hi_i32 s3, s2, 0x38e38e39
	s_lshr_b32 s8, s3, 31
	s_ashr_i32 s3, s3, 9
	s_add_i32 s3, s3, s8
	s_mulk_i32 s3, 0x900
	s_sub_i32 s3, s2, s3
	s_cmpk_gt_i32 s3, 0xff
	s_cselect_b64 s[8:9], -1, 0
	s_add_i32 s10, s3, 0xffffff00
	s_ashr_i32 s10, s10, 6
	v_cvt_f32_i32_e32 v24, s10
	s_and_b32 s10, s3, 63
	s_cmpk_lt_i32 s3, 0x100
	v_cvt_f32_ubyte0_e32 v25, s10
	s_cbranch_scc1 .LBB0_996
	v_lshl_add_u64 v[16:17], v[10:11], 0, s[4:5]
	s_mov_b64 s[22:23], 0x800
	v_lshl_add_u64 v[122:123], v[16:17], 0, s[22:23]
	global_load_dwordx4 v[108:111], v[122:123], off
	global_load_dwordx4 v[112:115], v[122:123], off offset:32
	s_mov_b64 s[10:11], 0
	v_mov_b32_e32 v13, v70
	v_mov_b32_e32 v15, v58
.LBB0_994:
	v_and_b32_e32 v0, 2, v15
	v_cmp_eq_u32_e32 vcc, 0, v0
	s_cmp_lg_u64 s[10:11], 0
	s_cbranch_scc1 .Lp3_pass2
	global_load_dwordx4 v[4:7], v[16:17], off
	global_load_dwordx4 v[0:3], v[16:17], off offset:32
	s_branch .Lp3_loaded
.Lp3_pass2:
	v_mov_b32_e32 v4, v108
	v_mov_b32_e32 v5, v109
	v_mov_b32_e32 v6, v110
	v_mov_b32_e32 v7, v111
	v_mov_b32_e32 v0, v112
	v_mov_b32_e32 v1, v113
	v_mov_b32_e32 v2, v114
	v_mov_b32_e32 v3, v115
.Lp3_loaded:
	v_and_b32_e32 v23, 8, v13
	v_cvt_f32_ubyte0_e32 v18, v23
	v_mul_f32_e32 v18, 0xbf549a78, v18
	v_exp_f32_e32 v18, v18
	v_cndmask_b32_e32 v22, v25, v24, vcc
	s_mov_b64 s[12:13], 0x800
	v_cmp_lt_u32_e32 vcc, 31, v15
	v_mul_f32_e32 v18, 0.15915494, v18
	v_mul_f32_e32 v19, v22, v18
	v_floor_f32_e32 v19, v19
	v_fma_f32 v19, v22, v18, -v19
	v_sin_f32_e32 v18, v19
	v_cos_f32_e32 v20, v19
	v_or_b32_e32 v19, 1, v23
	v_cvt_f32_ubyte0_e32 v19, v19
	v_mul_f32_e32 v19, 0xbf549a78, v19
	v_exp_f32_e32 v19, v19
	v_add_u32_e32 v13, 0x200, v13
	s_or_b64 s[10:11], vcc, s[10:11]
	v_mul_f32_e32 v19, 0.15915494, v19
	v_mul_f32_e32 v21, v22, v19
	v_floor_f32_e32 v21, v21
	v_fma_f32 v21, v22, v19, -v21
	v_sin_f32_e32 v19, v21
	v_cos_f32_e32 v21, v21
	s_waitcnt vmcnt(0)
	v_lshlrev_b32_e32 v26, 16, v4
	v_lshlrev_b32_e32 v28, 16, v0
	v_and_b32_e32 v29, 0xffff0000, v0
	v_and_b32_e32 v27, 0xffff0000, v4
	v_pk_mul_f32 v[30:31], v[20:21], v[28:29]
	s_nop 0
	v_pk_fma_f32 v[30:31], v[18:19], v[26:27], v[30:31]
	v_pk_mul_f32 v[18:19], v[18:19], v[28:29]
	v_lshlrev_b32_e32 v28, 16, v1
	v_pk_fma_f32 v[18:19], v[20:21], v[26:27], v[18:19] neg_lo:[0,0,1] neg_hi:[0,0,1]
	v_and_b32_e32 v29, 0xffff0000, v1
	v_cvt_pk_bf16_f32 v4, v18, v19
	v_or_b32_e32 v18, 2, v23
	v_cvt_f32_ubyte0_e32 v18, v18
	v_mul_f32_e32 v18, 0xbf549a78, v18
	v_exp_f32_e32 v18, v18
	v_cvt_pk_bf16_f32 v0, v30, v31
	v_lshlrev_b32_e32 v26, 16, v5
	v_and_b32_e32 v27, 0xffff0000, v5
	v_mul_f32_e32 v18, 0.15915494, v18
	v_mul_f32_e32 v19, v22, v18
	v_floor_f32_e32 v19, v19
	v_fma_f32 v19, v22, v18, -v19
	v_sin_f32_e32 v18, v19
	v_cos_f32_e32 v20, v19
	v_or_b32_e32 v19, 3, v23
	v_cvt_f32_ubyte0_e32 v19, v19
	v_mul_f32_e32 v19, 0xbf549a78, v19
	v_exp_f32_e32 v19, v19
	s_nop 0
	v_mul_f32_e32 v19, 0.15915494, v19
	v_mul_f32_e32 v21, v22, v19
	v_floor_f32_e32 v21, v21
	v_fma_f32 v21, v22, v19, -v21
	v_sin_f32_e32 v19, v21
	v_cos_f32_e32 v21, v21
	s_nop 0
	v_pk_mul_f32 v[30:31], v[20:21], v[28:29]
	s_nop 0
	v_pk_fma_f32 v[30:31], v[18:19], v[26:27], v[30:31]
	v_pk_mul_f32 v[18:19], v[18:19], v[28:29]
	v_lshlrev_b32_e32 v28, 16, v2
	v_pk_fma_f32 v[18:19], v[20:21], v[26:27], v[18:19] neg_lo:[0,0,1] neg_hi:[0,0,1]
	v_and_b32_e32 v29, 0xffff0000, v2
	v_cvt_pk_bf16_f32 v5, v18, v19
	v_or_b32_e32 v18, 4, v23
	v_cvt_f32_ubyte0_e32 v18, v18
	v_mul_f32_e32 v18, 0xbf549a78, v18
	v_exp_f32_e32 v18, v18
	v_cvt_pk_bf16_f32 v1, v30, v31
	v_lshlrev_b32_e32 v26, 16, v6
	v_and_b32_e32 v27, 0xffff0000, v6
	v_mul_f32_e32 v18, 0.15915494, v18
	v_mul_f32_e32 v19, v22, v18
	v_floor_f32_e32 v19, v19
	v_fma_f32 v19, v22, v18, -v19
	v_sin_f32_e32 v18, v19
	v_cos_f32_e32 v20, v19
	v_or_b32_e32 v19, 5, v23
	v_cvt_f32_ubyte0_e32 v19, v19
	v_mul_f32_e32 v19, 0xbf549a78, v19
	v_exp_f32_e32 v19, v19
	s_nop 0
	v_mul_f32_e32 v19, 0.15915494, v19
	v_mul_f32_e32 v21, v22, v19
	v_floor_f32_e32 v21, v21
	v_fma_f32 v21, v22, v19, -v21
	v_sin_f32_e32 v19, v21
	v_cos_f32_e32 v21, v21
	s_nop 0
	v_pk_mul_f32 v[30:31], v[20:21], v[28:29]
	s_nop 0
	v_pk_fma_f32 v[30:31], v[18:19], v[26:27], v[30:31]
	v_pk_mul_f32 v[18:19], v[18:19], v[28:29]
	v_cvt_pk_bf16_f32 v2, v30, v31
	v_pk_fma_f32 v[18:19], v[20:21], v[26:27], v[18:19] neg_lo:[0,0,1] neg_hi:[0,0,1]
	v_lshlrev_b32_e32 v26, 16, v3
	v_cvt_pk_bf16_f32 v6, v18, v19
	v_or_b32_e32 v18, 6, v23
	v_cvt_f32_ubyte0_e32 v18, v18
	v_mul_f32_e32 v18, 0xbf549a78, v18
	v_exp_f32_e32 v18, v18
	v_and_b32_e32 v27, 0xffff0000, v3
	v_mul_f32_e32 v18, 0.15915494, v18
	v_mul_f32_e32 v19, v22, v18
	v_floor_f32_e32 v19, v19
	v_fma_f32 v19, v22, v18, -v19
	v_sin_f32_e32 v18, v19
	v_cos_f32_e32 v20, v19
	v_or_b32_e32 v19, 7, v23
	v_cvt_f32_ubyte0_e32 v19, v19
	v_mul_f32_e32 v19, 0xbf549a78, v19
	v_exp_f32_e32 v19, v19
	v_and_b32_e32 v23, 0xffff0000, v7
	v_mul_f32_e32 v19, 0.15915494, v19
	v_mul_f32_e32 v21, v22, v19
	v_floor_f32_e32 v21, v21
	v_fma_f32 v21, v22, v19, -v21
	v_sin_f32_e32 v19, v21
	v_cos_f32_e32 v21, v21
	v_lshlrev_b32_e32 v22, 16, v7
	v_pk_mul_f32 v[28:29], v[20:21], v[26:27]
	s_nop 0
	v_pk_fma_f32 v[28:29], v[18:19], v[22:23], v[28:29]
	v_pk_mul_f32 v[18:19], v[18:19], v[26:27]
	v_cvt_pk_bf16_f32 v3, v28, v29
	v_pk_fma_f32 v[18:19], v[20:21], v[22:23], v[18:19] neg_lo:[0,0,1] neg_hi:[0,0,1]
	s_nop 0
	v_cvt_pk_bf16_f32 v7, v18, v19
	global_store_dwordx4 v[16:17], v[4:7], off sc1
	global_store_dwordx4 v[16:17], v[0:3], off offset:32 sc1
	v_lshl_add_u64 v[16:17], v[16:17], 0, s[12:13]
	s_nop 0
	v_add_u32_e32 v0, 64, v15
	v_mov_b32_e32 v15, v0
	s_andn2_b64 exec, exec, s[10:11]
	s_cbranch_execnz .LBB0_994
	s_or_b64 exec, exec, s[10:11]
.LBB0_996:
	v_readlane_b32 s10, v253, 56
	v_readlane_b32 s11, v253, 57
	s_add_u32 s4, s10, s4
	s_addc_u32 s5, s11, s5
	v_lshl_add_u64 v[0:1], s[4:5], 0, v[176:177]
	v_mov_b32_e32 v13, v177
	v_lshl_add_u64 v[0:1], v[0:1], 0, v[12:13]
	v_mov_b32_e32 v15, v177
	v_lshl_add_u64 v[2:3], v[0:1], 0, v[14:15]
	s_mov_b64 s[4:5], 0x1600
	v_lshl_add_u64 v[0:1], v[2:3], 0, s[4:5]
	v_add_co_u32_e32 v2, vcc, 0x1000, v2
	v_cndmask_b32_e64 v13, v25, v24, s[6:7]
	s_nop 0
	v_addc_co_u32_e32 v3, vcc, 0, v3, vcc
	s_andn2_b64 vcc, exec, s[8:9]
	s_waitcnt vmcnt(0)
	v_mov_b32_e32 v26, v100
	v_mov_b32_e32 v27, v101
	v_mov_b32_e32 v28, v102
	v_mov_b32_e32 v29, v103
	v_mov_b32_e32 v30, v104
	v_mov_b32_e32 v31, v105
	v_mov_b32_e32 v32, v106
	v_mov_b32_e32 v33, v107
	v_mov_b32_e32 v25, v124
	v_and_b32_e32 v3, 0xffff0000, v26
	v_and_b32_e32 v2, 0xffff0000, v30
	v_lshlrev_b32_e32 v7, 16, v27
	v_and_b32_e32 v5, 0xffff0000, v27
	v_lshlrev_b32_e32 v27, 16, v26
	v_lshlrev_b32_e32 v26, 16, v30
	v_lshlrev_b32_e32 v6, 16, v31
	v_and_b32_e32 v4, 0xffff0000, v31
	v_lshlrev_b32_e32 v19, 16, v28
	v_and_b32_e32 v17, 0xffff0000, v28
	v_lshlrev_b32_e32 v23, 16, v29
	v_and_b32_e32 v21, 0xffff0000, v29
	v_pk_mul_f32 v[28:29], v[2:3], v[2:3]
	v_pk_mul_f32 v[30:31], v[26:27], v[26:27]
	v_lshlrev_b32_e32 v18, 16, v32
	v_and_b32_e32 v16, 0xffff0000, v32
	v_lshlrev_b32_e32 v22, 16, v33
	v_and_b32_e32 v20, 0xffff0000, v33
	v_pk_mul_f32 v[32:33], v[6:7], v[6:7]
	v_add_f32_e32 v24, v29, v28
	v_add_f32_e32 v28, v31, v30
	v_pk_mul_f32 v[34:35], v[4:5], v[4:5]
	v_mov_b32_e32 v38, v18
	v_mov_b32_e32 v39, v16
	v_add_f32_e32 v24, v28, v24
	v_add_f32_e32 v28, v33, v32
	v_mov_b32_e32 v36, v19
	v_mov_b32_e32 v37, v17
	v_pk_mul_f32 v[38:39], v[38:39], v[38:39]
	v_add_f32_e32 v15, v35, v34
	v_add_f32_e32 v24, v24, v28
	v_pk_fma_f32 v[36:37], v[36:37], v[36:37], v[38:39]
	v_mov_b32_e32 v40, v22
	v_mov_b32_e32 v41, v20
	v_add_f32_e32 v15, v24, v15
	v_mov_b32_e32 v38, v23
	v_mov_b32_e32 v39, v21
	v_pk_mul_f32 v[40:41], v[40:41], v[40:41]
	v_add_f32_e32 v15, v15, v36
	v_pk_fma_f32 v[38:39], v[38:39], v[38:39], v[40:41]
	v_add_f32_e32 v15, v15, v37
	v_add_f32_e32 v15, v15, v38
	v_add_f32_e32 v15, v15, v39
	ds_bpermute_b32 v24, v59, v15
	v_cndmask_b32_e64 v30, 0, 1, s[8:9]
	v_mov_b32_e32 v29, 0
	v_mov_b32_e32 v28, 1.0
	v_cmp_ne_u32_e64 s[4:5], 1, v30
	s_waitcnt lgkmcnt(0)
	v_add_f32_e32 v15, v15, v24
	ds_bpermute_b32 v24, v60, v15
	v_mov_b32_e32 v32, 1.0
	v_mov_b32_e32 v33, 0
	s_waitcnt lgkmcnt(0)
	v_add_f32_e32 v15, v15, v24
	global_load_dword v24, v[8:9], off offset:128
	ds_bpermute_b32 v71, v61, v15
	s_cbranch_vccnz .LBB0_998
	v_mul_f32_e32 v30, v13, v62
	v_floor_f32_e32 v30, v30
	v_fma_f32 v30, v13, v62, -v30
	v_sin_f32_e32 v33, v30
	v_cos_f32_e32 v32, v30
